# retc_tile epilogue hand-rescheduled (32 gain/gate loads in flight instead of serialized behind stores)
# speedup vs baseline: 1.0528x; 1.0063x over previous
.LBB0_891:
	s_or_b64 exec, exec, s[0:1]
	v_lshl_or_b32 v2, v220, 7, v224
	s_lshl_b32 s0, s6, 1
	s_mov_b32 s1, s7
	v_ashrrev_i32_e32 v3, 31, v2
	v_lshl_add_u64 v[4:5], v[182:183], 0, s[0:1]
	v_lshlrev_b64 v[14:15], 1, v[2:3]
	v_lshl_add_u64 v[8:9], v[4:5], 0, v[14:15]
	v_add_co_u32_e32 v4, vcc, s31, v8
	s_waitcnt lgkmcnt(0)
	s_nop 0
	v_addc_co_u32_e32 v5, vcc, 0, v9, vcc
	s_barrier
	v_readlane_b32 s76, v252, 14
	s_lshl_b32 s2, s6, 2
	v_readlane_b32 s88, v252, 26
	v_readlane_b32 s89, v252, 27
	s_add_u32 s2, s88, s2
	s_addc_u32 s3, s89, 0
	v_lshl_add_u64 v[6:7], v[2:3], 2, s[2:3]
	v_lshlrev_b32_e32 v82, 1, v216
	v_mov_b64_e32 v[80:81], s[92:93]
	v_bitop3_b32 v0, v82, s29, v0 bitop3:0x36
	v_mad_u64_u32 v[80:81], s[2:3], v218, s26, v[80:81]
	v_lshl_add_u32 v82, v0, 2, 0
	v_mov_b32_e32 v0, v81
	v_add_u32_e32 v81, 0x12000, v82
	ds_read_b64 v[82:83], v81
	v_mad_u64_u32 v[84:85], s[2:3], v219, s26, v[0:1]
	v_mov_b32_e32 v81, v84
	v_lshl_add_u64 v[80:81], v[80:81], 0, s[0:1]
	s_waitcnt lgkmcnt(0)
	v_pk_add_f32 v[10:11], v[10:11], v[82:83]
	v_lshl_add_u64 v[8:9], v[8:9], 0, s[10:11]
	v_pk_mul_f32 v[82:83], v[10:11], s[8:9] op_sel_hi:[1,0]
	v_fma_f32 v0, -v82, v82, v83
	v_max_f32_e32 v0, 0, v0
	v_add_f32_e32 v0, 0x358637bd, v0
	v_mul_f32_e32 v10, 0x4b800000, v0
	v_cmp_gt_f32_e32 vcc, s30, v0
	v_cndmask_b32_e32 v0, v0, v10, vcc
	v_rsq_f32_e32 v0, v0
	v_lshl_add_u64 v[10:11], v[80:81], 0, v[14:15]
	v_mul_f32_e32 v84, 0x45800000, v0
	v_cndmask_b32_e32 v0, v0, v84, vcc
	v_readlane_b32 s77, v252, 15
	v_readlane_b32 s78, v252, 16
	v_readlane_b32 s79, v252, 17
	v_readlane_b32 s80, v252, 18
	v_readlane_b32 s81, v252, 19
	v_readlane_b32 s82, v252, 20
	v_readlane_b32 s83, v252, 21
	v_readlane_b32 s84, v252, 22
	v_readlane_b32 s85, v252, 23
	v_readlane_b32 s86, v252, 24
	v_readlane_b32 s87, v252, 25
	v_readlane_b32 s90, v252, 28
	v_readlane_b32 s91, v252, 29
	global_load_dwordx4 v[90:93], v[6:7], off
	global_load_dwordx2 v[154:155], v[8:9], off
	global_load_dwordx4 v[94:97], v[6:7], off offset:32
	global_load_dwordx2 v[156:157], v[8:9], off offset:16
	global_load_dwordx4 v[98:101], v[6:7], off offset:64
	global_load_dwordx2 v[158:159], v[8:9], off offset:32
	global_load_dwordx4 v[102:105], v[6:7], off offset:96
	global_load_dwordx2 v[160:161], v[8:9], off offset:48
	global_load_dwordx4 v[106:109], v[6:7], off offset:128
	global_load_dwordx2 v[162:163], v[8:9], off offset:64
	global_load_dwordx4 v[110:113], v[6:7], off offset:160
	global_load_dwordx2 v[164:165], v[8:9], off offset:80
	global_load_dwordx4 v[114:117], v[6:7], off offset:192
	global_load_dwordx2 v[166:167], v[8:9], off offset:96
	global_load_dwordx4 v[118:121], v[6:7], off offset:224
	global_load_dwordx2 v[168:169], v[8:9], off offset:112
	global_load_dwordx4 v[122:125], v[6:7], off offset:256
	global_load_dwordx2 v[170:171], v[8:9], off offset:128
	global_load_dwordx4 v[126:129], v[6:7], off offset:288
	global_load_dwordx2 v[172:173], v[8:9], off offset:144
	global_load_dwordx4 v[130:133], v[6:7], off offset:320
	global_load_dwordx2 v[174:175], v[8:9], off offset:160
	global_load_dwordx4 v[134:137], v[6:7], off offset:352
	global_load_dwordx2 v[2:3], v[8:9], off offset:176
	global_load_dwordx4 v[138:141], v[6:7], off offset:384
	global_load_dwordx2 v[4:5], v[8:9], off offset:192
	global_load_dwordx4 v[142:145], v[6:7], off offset:416
	global_load_dwordx2 v[12:13], v[8:9], off offset:208
	global_load_dwordx4 v[146:149], v[6:7], off offset:448
	global_load_dwordx2 v[14:15], v[8:9], off offset:224
	global_load_dwordx4 v[150:153], v[6:7], off offset:480
	global_load_dwordx2 v[86:87], v[8:9], off offset:240
	s_waitcnt vmcnt(30)
	v_lshlrev_b32_e32 v184, 16, v154
	v_and_b32_e32 v185, 0xffff0000, v154
	v_lshlrev_b32_e32 v186, 16, v155
	v_and_b32_e32 v187, 0xffff0000, v155
	v_mul_f32_e32 v188, 0xbfb8aa3b, v184
	v_mul_f32_e32 v189, 0xbfb8aa3b, v185
	v_mul_f32_e32 v190, 0xbfb8aa3b, v186
	v_mul_f32_e32 v191, 0xbfb8aa3b, v187
	v_exp_f32_e32 v188, v188
	v_exp_f32_e32 v189, v189
	v_exp_f32_e32 v190, v190
	v_exp_f32_e32 v191, v191
	v_sub_f32_e32 v192, v64, v82
	v_sub_f32_e32 v193, v65, v82
	v_sub_f32_e32 v194, v66, v82
	v_sub_f32_e32 v195, v67, v82
	v_add_f32_e32 v188, 1.0, v188
	v_add_f32_e32 v189, 1.0, v189
	v_add_f32_e32 v190, 1.0, v190
	v_add_f32_e32 v191, 1.0, v191
	v_rcp_f32_e32 v188, v188
	v_rcp_f32_e32 v189, v189
	v_rcp_f32_e32 v190, v190
	v_rcp_f32_e32 v191, v191
	v_mul_f32_e32 v192, v192, v0
	v_mul_f32_e32 v193, v193, v0
	v_mul_f32_e32 v194, v194, v0
	v_mul_f32_e32 v195, v195, v0
	v_mul_f32_e32 v184, v184, v188
	v_mul_f32_e32 v185, v185, v189
	v_mul_f32_e32 v186, v186, v190
	v_mul_f32_e32 v187, v187, v191
	v_mul_f32_e32 v192, v90, v192
	v_mul_f32_e32 v193, v91, v193
	v_mul_f32_e32 v194, v92, v194
	v_mul_f32_e32 v195, v93, v195
	v_mul_f32_e32 v192, v192, v184
	v_mul_f32_e32 v193, v193, v185
	v_mul_f32_e32 v194, v194, v186
	v_mul_f32_e32 v195, v195, v187
	v_cvt_pk_bf16_f32 v192, v192, v193
	v_cvt_pk_bf16_f32 v193, v194, v195
	global_store_dwordx2 v[10:11], v[192:193], off
	s_waitcnt vmcnt(29)
	v_lshlrev_b32_e32 v184, 16, v156
	v_and_b32_e32 v185, 0xffff0000, v156
	v_lshlrev_b32_e32 v186, 16, v157
	v_and_b32_e32 v187, 0xffff0000, v157
	v_mul_f32_e32 v188, 0xbfb8aa3b, v184
	v_mul_f32_e32 v189, 0xbfb8aa3b, v185
	v_mul_f32_e32 v190, 0xbfb8aa3b, v186
	v_mul_f32_e32 v191, 0xbfb8aa3b, v187
	v_exp_f32_e32 v188, v188
	v_exp_f32_e32 v189, v189
	v_exp_f32_e32 v190, v190
	v_exp_f32_e32 v191, v191
	v_sub_f32_e32 v192, v68, v82
	v_sub_f32_e32 v193, v69, v82
	v_sub_f32_e32 v194, v70, v82
	v_sub_f32_e32 v195, v71, v82
	v_add_f32_e32 v188, 1.0, v188
	v_add_f32_e32 v189, 1.0, v189
	v_add_f32_e32 v190, 1.0, v190
	v_add_f32_e32 v191, 1.0, v191
	v_rcp_f32_e32 v188, v188
	v_rcp_f32_e32 v189, v189
	v_rcp_f32_e32 v190, v190
	v_rcp_f32_e32 v191, v191
	v_mul_f32_e32 v192, v192, v0
	v_mul_f32_e32 v193, v193, v0
	v_mul_f32_e32 v194, v194, v0
	v_mul_f32_e32 v195, v195, v0
	v_mul_f32_e32 v184, v184, v188
	v_mul_f32_e32 v185, v185, v189
	v_mul_f32_e32 v186, v186, v190
	v_mul_f32_e32 v187, v187, v191
	v_mul_f32_e32 v192, v94, v192
	v_mul_f32_e32 v193, v95, v193
	v_mul_f32_e32 v194, v96, v194
	v_mul_f32_e32 v195, v97, v195
	v_mul_f32_e32 v192, v192, v184
	v_mul_f32_e32 v193, v193, v185
	v_mul_f32_e32 v194, v194, v186
	v_mul_f32_e32 v195, v195, v187
	v_cvt_pk_bf16_f32 v192, v192, v193
	v_cvt_pk_bf16_f32 v193, v194, v195
	global_store_dwordx2 v[10:11], v[192:193], off offset:16
	s_waitcnt vmcnt(28)
	v_lshlrev_b32_e32 v184, 16, v158
	v_and_b32_e32 v185, 0xffff0000, v158
	v_lshlrev_b32_e32 v186, 16, v159
	v_and_b32_e32 v187, 0xffff0000, v159
	v_mul_f32_e32 v188, 0xbfb8aa3b, v184
	v_mul_f32_e32 v189, 0xbfb8aa3b, v185
	v_mul_f32_e32 v190, 0xbfb8aa3b, v186
	v_mul_f32_e32 v191, 0xbfb8aa3b, v187
	v_exp_f32_e32 v188, v188
	v_exp_f32_e32 v189, v189
	v_exp_f32_e32 v190, v190
	v_exp_f32_e32 v191, v191
	v_sub_f32_e32 v192, v72, v82
	v_sub_f32_e32 v193, v73, v82
	v_sub_f32_e32 v194, v74, v82
	v_sub_f32_e32 v195, v75, v82
	v_add_f32_e32 v188, 1.0, v188
	v_add_f32_e32 v189, 1.0, v189
	v_add_f32_e32 v190, 1.0, v190
	v_add_f32_e32 v191, 1.0, v191
	v_rcp_f32_e32 v188, v188
	v_rcp_f32_e32 v189, v189
	v_rcp_f32_e32 v190, v190
	v_rcp_f32_e32 v191, v191
	v_mul_f32_e32 v192, v192, v0
	v_mul_f32_e32 v193, v193, v0
	v_mul_f32_e32 v194, v194, v0
	v_mul_f32_e32 v195, v195, v0
	v_mul_f32_e32 v184, v184, v188
	v_mul_f32_e32 v185, v185, v189
	v_mul_f32_e32 v186, v186, v190
	v_mul_f32_e32 v187, v187, v191
	v_mul_f32_e32 v192, v98, v192
	v_mul_f32_e32 v193, v99, v193
	v_mul_f32_e32 v194, v100, v194
	v_mul_f32_e32 v195, v101, v195
	v_mul_f32_e32 v192, v192, v184
	v_mul_f32_e32 v193, v193, v185
	v_mul_f32_e32 v194, v194, v186
	v_mul_f32_e32 v195, v195, v187
	v_cvt_pk_bf16_f32 v192, v192, v193
	v_cvt_pk_bf16_f32 v193, v194, v195
	global_store_dwordx2 v[10:11], v[192:193], off offset:32
	s_waitcnt vmcnt(27)
	v_lshlrev_b32_e32 v184, 16, v160
	v_and_b32_e32 v185, 0xffff0000, v160
	v_lshlrev_b32_e32 v186, 16, v161
	v_and_b32_e32 v187, 0xffff0000, v161
	v_mul_f32_e32 v188, 0xbfb8aa3b, v184
	v_mul_f32_e32 v189, 0xbfb8aa3b, v185
	v_mul_f32_e32 v190, 0xbfb8aa3b, v186
	v_mul_f32_e32 v191, 0xbfb8aa3b, v187
	v_exp_f32_e32 v188, v188
	v_exp_f32_e32 v189, v189
	v_exp_f32_e32 v190, v190
	v_exp_f32_e32 v191, v191
	v_sub_f32_e32 v192, v76, v82
	v_sub_f32_e32 v193, v77, v82
	v_sub_f32_e32 v194, v78, v82
	v_sub_f32_e32 v195, v79, v82
	v_add_f32_e32 v188, 1.0, v188
	v_add_f32_e32 v189, 1.0, v189
	v_add_f32_e32 v190, 1.0, v190
	v_add_f32_e32 v191, 1.0, v191
	v_rcp_f32_e32 v188, v188
	v_rcp_f32_e32 v189, v189
	v_rcp_f32_e32 v190, v190
	v_rcp_f32_e32 v191, v191
	v_mul_f32_e32 v192, v192, v0
	v_mul_f32_e32 v193, v193, v0
	v_mul_f32_e32 v194, v194, v0
	v_mul_f32_e32 v195, v195, v0
	v_mul_f32_e32 v184, v184, v188
	v_mul_f32_e32 v185, v185, v189
	v_mul_f32_e32 v186, v186, v190
	v_mul_f32_e32 v187, v187, v191
	v_mul_f32_e32 v192, v102, v192
	v_mul_f32_e32 v193, v103, v193
	v_mul_f32_e32 v194, v104, v194
	v_mul_f32_e32 v195, v105, v195
	v_mul_f32_e32 v192, v192, v184
	v_mul_f32_e32 v193, v193, v185
	v_mul_f32_e32 v194, v194, v186
	v_mul_f32_e32 v195, v195, v187
	v_cvt_pk_bf16_f32 v192, v192, v193
	v_cvt_pk_bf16_f32 v193, v194, v195
	global_store_dwordx2 v[10:11], v[192:193], off offset:48
	s_waitcnt vmcnt(26)
	v_lshlrev_b32_e32 v184, 16, v162
	v_and_b32_e32 v185, 0xffff0000, v162
	v_lshlrev_b32_e32 v186, 16, v163
	v_and_b32_e32 v187, 0xffff0000, v163
	v_mul_f32_e32 v188, 0xbfb8aa3b, v184
	v_mul_f32_e32 v189, 0xbfb8aa3b, v185
	v_mul_f32_e32 v190, 0xbfb8aa3b, v186
	v_mul_f32_e32 v191, 0xbfb8aa3b, v187
	v_exp_f32_e32 v188, v188
	v_exp_f32_e32 v189, v189
	v_exp_f32_e32 v190, v190
	v_exp_f32_e32 v191, v191
	v_sub_f32_e32 v192, v48, v82
	v_sub_f32_e32 v193, v49, v82
	v_sub_f32_e32 v194, v50, v82
	v_sub_f32_e32 v195, v51, v82
	v_add_f32_e32 v188, 1.0, v188
	v_add_f32_e32 v189, 1.0, v189
	v_add_f32_e32 v190, 1.0, v190
	v_add_f32_e32 v191, 1.0, v191
	v_rcp_f32_e32 v188, v188
	v_rcp_f32_e32 v189, v189
	v_rcp_f32_e32 v190, v190
	v_rcp_f32_e32 v191, v191
	v_mul_f32_e32 v192, v192, v0
	v_mul_f32_e32 v193, v193, v0
	v_mul_f32_e32 v194, v194, v0
	v_mul_f32_e32 v195, v195, v0
	v_mul_f32_e32 v184, v184, v188
	v_mul_f32_e32 v185, v185, v189
	v_mul_f32_e32 v186, v186, v190
	v_mul_f32_e32 v187, v187, v191
	v_mul_f32_e32 v192, v106, v192
	v_mul_f32_e32 v193, v107, v193
	v_mul_f32_e32 v194, v108, v194
	v_mul_f32_e32 v195, v109, v195
	v_mul_f32_e32 v192, v192, v184
	v_mul_f32_e32 v193, v193, v185
	v_mul_f32_e32 v194, v194, v186
	v_mul_f32_e32 v195, v195, v187
	v_cvt_pk_bf16_f32 v192, v192, v193
	v_cvt_pk_bf16_f32 v193, v194, v195
	global_store_dwordx2 v[10:11], v[192:193], off offset:64
	s_waitcnt vmcnt(25)
	v_lshlrev_b32_e32 v184, 16, v164
	v_and_b32_e32 v185, 0xffff0000, v164
	v_lshlrev_b32_e32 v186, 16, v165
	v_and_b32_e32 v187, 0xffff0000, v165
	v_mul_f32_e32 v188, 0xbfb8aa3b, v184
	v_mul_f32_e32 v189, 0xbfb8aa3b, v185
	v_mul_f32_e32 v190, 0xbfb8aa3b, v186
	v_mul_f32_e32 v191, 0xbfb8aa3b, v187
	v_exp_f32_e32 v188, v188
	v_exp_f32_e32 v189, v189
	v_exp_f32_e32 v190, v190
	v_exp_f32_e32 v191, v191
	v_sub_f32_e32 v192, v52, v82
	v_sub_f32_e32 v193, v53, v82
	v_sub_f32_e32 v194, v54, v82
	v_sub_f32_e32 v195, v55, v82
	v_add_f32_e32 v188, 1.0, v188
	v_add_f32_e32 v189, 1.0, v189
	v_add_f32_e32 v190, 1.0, v190
	v_add_f32_e32 v191, 1.0, v191
	v_rcp_f32_e32 v188, v188
	v_rcp_f32_e32 v189, v189
	v_rcp_f32_e32 v190, v190
	v_rcp_f32_e32 v191, v191
	v_mul_f32_e32 v192, v192, v0
	v_mul_f32_e32 v193, v193, v0
	v_mul_f32_e32 v194, v194, v0
	v_mul_f32_e32 v195, v195, v0
	v_mul_f32_e32 v184, v184, v188
	v_mul_f32_e32 v185, v185, v189
	v_mul_f32_e32 v186, v186, v190
	v_mul_f32_e32 v187, v187, v191
	v_mul_f32_e32 v192, v110, v192
	v_mul_f32_e32 v193, v111, v193
	v_mul_f32_e32 v194, v112, v194
	v_mul_f32_e32 v195, v113, v195
	v_mul_f32_e32 v192, v192, v184
	v_mul_f32_e32 v193, v193, v185
	v_mul_f32_e32 v194, v194, v186
	v_mul_f32_e32 v195, v195, v187
	v_cvt_pk_bf16_f32 v192, v192, v193
	v_cvt_pk_bf16_f32 v193, v194, v195
	global_store_dwordx2 v[10:11], v[192:193], off offset:80
	s_waitcnt vmcnt(24)
	v_lshlrev_b32_e32 v184, 16, v166
	v_and_b32_e32 v185, 0xffff0000, v166
	v_lshlrev_b32_e32 v186, 16, v167
	v_and_b32_e32 v187, 0xffff0000, v167
	v_mul_f32_e32 v188, 0xbfb8aa3b, v184
	v_mul_f32_e32 v189, 0xbfb8aa3b, v185
	v_mul_f32_e32 v190, 0xbfb8aa3b, v186
	v_mul_f32_e32 v191, 0xbfb8aa3b, v187
	v_exp_f32_e32 v188, v188
	v_exp_f32_e32 v189, v189
	v_exp_f32_e32 v190, v190
	v_exp_f32_e32 v191, v191
	v_sub_f32_e32 v192, v56, v82
	v_sub_f32_e32 v193, v57, v82
	v_sub_f32_e32 v194, v58, v82
	v_sub_f32_e32 v195, v59, v82
	v_add_f32_e32 v188, 1.0, v188
	v_add_f32_e32 v189, 1.0, v189
	v_add_f32_e32 v190, 1.0, v190
	v_add_f32_e32 v191, 1.0, v191
	v_rcp_f32_e32 v188, v188
	v_rcp_f32_e32 v189, v189
	v_rcp_f32_e32 v190, v190
	v_rcp_f32_e32 v191, v191
	v_mul_f32_e32 v192, v192, v0
	v_mul_f32_e32 v193, v193, v0
	v_mul_f32_e32 v194, v194, v0
	v_mul_f32_e32 v195, v195, v0
	v_mul_f32_e32 v184, v184, v188
	v_mul_f32_e32 v185, v185, v189
	v_mul_f32_e32 v186, v186, v190
	v_mul_f32_e32 v187, v187, v191
	v_mul_f32_e32 v192, v114, v192
	v_mul_f32_e32 v193, v115, v193
	v_mul_f32_e32 v194, v116, v194
	v_mul_f32_e32 v195, v117, v195
	v_mul_f32_e32 v192, v192, v184
	v_mul_f32_e32 v193, v193, v185
	v_mul_f32_e32 v194, v194, v186
	v_mul_f32_e32 v195, v195, v187
	v_cvt_pk_bf16_f32 v192, v192, v193
	v_cvt_pk_bf16_f32 v193, v194, v195
	global_store_dwordx2 v[10:11], v[192:193], off offset:96
	s_waitcnt vmcnt(23)
	v_lshlrev_b32_e32 v184, 16, v168
	v_and_b32_e32 v185, 0xffff0000, v168
	v_lshlrev_b32_e32 v186, 16, v169
	v_and_b32_e32 v187, 0xffff0000, v169
	v_mul_f32_e32 v188, 0xbfb8aa3b, v184
	v_mul_f32_e32 v189, 0xbfb8aa3b, v185
	v_mul_f32_e32 v190, 0xbfb8aa3b, v186
	v_mul_f32_e32 v191, 0xbfb8aa3b, v187
	v_exp_f32_e32 v188, v188
	v_exp_f32_e32 v189, v189
	v_exp_f32_e32 v190, v190
	v_exp_f32_e32 v191, v191
	v_sub_f32_e32 v192, v60, v82
	v_sub_f32_e32 v193, v61, v82
	v_sub_f32_e32 v194, v62, v82
	v_sub_f32_e32 v195, v63, v82
	v_add_f32_e32 v188, 1.0, v188
	v_add_f32_e32 v189, 1.0, v189
	v_add_f32_e32 v190, 1.0, v190
	v_add_f32_e32 v191, 1.0, v191
	v_rcp_f32_e32 v188, v188
	v_rcp_f32_e32 v189, v189
	v_rcp_f32_e32 v190, v190
	v_rcp_f32_e32 v191, v191
	v_mul_f32_e32 v192, v192, v0
	v_mul_f32_e32 v193, v193, v0
	v_mul_f32_e32 v194, v194, v0
	v_mul_f32_e32 v195, v195, v0
	v_mul_f32_e32 v184, v184, v188
	v_mul_f32_e32 v185, v185, v189
	v_mul_f32_e32 v186, v186, v190
	v_mul_f32_e32 v187, v187, v191
	v_mul_f32_e32 v192, v118, v192
	v_mul_f32_e32 v193, v119, v193
	v_mul_f32_e32 v194, v120, v194
	v_mul_f32_e32 v195, v121, v195
	v_mul_f32_e32 v192, v192, v184
	v_mul_f32_e32 v193, v193, v185
	v_mul_f32_e32 v194, v194, v186
	v_mul_f32_e32 v195, v195, v187
	v_cvt_pk_bf16_f32 v192, v192, v193
	v_cvt_pk_bf16_f32 v193, v194, v195
	global_store_dwordx2 v[10:11], v[192:193], off offset:112
	s_waitcnt vmcnt(22)
	v_lshlrev_b32_e32 v184, 16, v170
	v_and_b32_e32 v185, 0xffff0000, v170
	v_lshlrev_b32_e32 v186, 16, v171
	v_and_b32_e32 v187, 0xffff0000, v171
	v_mul_f32_e32 v188, 0xbfb8aa3b, v184
	v_mul_f32_e32 v189, 0xbfb8aa3b, v185
	v_mul_f32_e32 v190, 0xbfb8aa3b, v186
	v_mul_f32_e32 v191, 0xbfb8aa3b, v187
	v_exp_f32_e32 v188, v188
	v_exp_f32_e32 v189, v189
	v_exp_f32_e32 v190, v190
	v_exp_f32_e32 v191, v191
	v_sub_f32_e32 v192, v32, v82
	v_sub_f32_e32 v193, v33, v82
	v_sub_f32_e32 v194, v34, v82
	v_sub_f32_e32 v195, v35, v82
	v_add_f32_e32 v188, 1.0, v188
	v_add_f32_e32 v189, 1.0, v189
	v_add_f32_e32 v190, 1.0, v190
	v_add_f32_e32 v191, 1.0, v191
	v_rcp_f32_e32 v188, v188
	v_rcp_f32_e32 v189, v189
	v_rcp_f32_e32 v190, v190
	v_rcp_f32_e32 v191, v191
	v_mul_f32_e32 v192, v192, v0
	v_mul_f32_e32 v193, v193, v0
	v_mul_f32_e32 v194, v194, v0
	v_mul_f32_e32 v195, v195, v0
	v_mul_f32_e32 v184, v184, v188
	v_mul_f32_e32 v185, v185, v189
	v_mul_f32_e32 v186, v186, v190
	v_mul_f32_e32 v187, v187, v191
	v_mul_f32_e32 v192, v122, v192
	v_mul_f32_e32 v193, v123, v193
	v_mul_f32_e32 v194, v124, v194
	v_mul_f32_e32 v195, v125, v195
	v_mul_f32_e32 v192, v192, v184
	v_mul_f32_e32 v193, v193, v185
	v_mul_f32_e32 v194, v194, v186
	v_mul_f32_e32 v195, v195, v187
	v_cvt_pk_bf16_f32 v192, v192, v193
	v_cvt_pk_bf16_f32 v193, v194, v195
	global_store_dwordx2 v[10:11], v[192:193], off offset:128
	s_waitcnt vmcnt(21)
	v_lshlrev_b32_e32 v184, 16, v172
	v_and_b32_e32 v185, 0xffff0000, v172
	v_lshlrev_b32_e32 v186, 16, v173
	v_and_b32_e32 v187, 0xffff0000, v173
	v_mul_f32_e32 v188, 0xbfb8aa3b, v184
	v_mul_f32_e32 v189, 0xbfb8aa3b, v185
	v_mul_f32_e32 v190, 0xbfb8aa3b, v186
	v_mul_f32_e32 v191, 0xbfb8aa3b, v187
	v_exp_f32_e32 v188, v188
	v_exp_f32_e32 v189, v189
	v_exp_f32_e32 v190, v190
	v_exp_f32_e32 v191, v191
	v_sub_f32_e32 v192, v36, v82
	v_sub_f32_e32 v193, v37, v82
	v_sub_f32_e32 v194, v38, v82
	v_sub_f32_e32 v195, v39, v82
	v_add_f32_e32 v188, 1.0, v188
	v_add_f32_e32 v189, 1.0, v189
	v_add_f32_e32 v190, 1.0, v190
	v_add_f32_e32 v191, 1.0, v191
	v_rcp_f32_e32 v188, v188
	v_rcp_f32_e32 v189, v189
	v_rcp_f32_e32 v190, v190
	v_rcp_f32_e32 v191, v191
	v_mul_f32_e32 v192, v192, v0
	v_mul_f32_e32 v193, v193, v0
	v_mul_f32_e32 v194, v194, v0
	v_mul_f32_e32 v195, v195, v0
	v_mul_f32_e32 v184, v184, v188
	v_mul_f32_e32 v185, v185, v189
	v_mul_f32_e32 v186, v186, v190
	v_mul_f32_e32 v187, v187, v191
	v_mul_f32_e32 v192, v126, v192
	v_mul_f32_e32 v193, v127, v193
	v_mul_f32_e32 v194, v128, v194
	v_mul_f32_e32 v195, v129, v195
	v_mul_f32_e32 v192, v192, v184
	v_mul_f32_e32 v193, v193, v185
	v_mul_f32_e32 v194, v194, v186
	v_mul_f32_e32 v195, v195, v187
	v_cvt_pk_bf16_f32 v192, v192, v193
	v_cvt_pk_bf16_f32 v193, v194, v195
	global_store_dwordx2 v[10:11], v[192:193], off offset:144
	s_waitcnt vmcnt(20)
	v_lshlrev_b32_e32 v184, 16, v174
	v_and_b32_e32 v185, 0xffff0000, v174
	v_lshlrev_b32_e32 v186, 16, v175
	v_and_b32_e32 v187, 0xffff0000, v175
	v_mul_f32_e32 v188, 0xbfb8aa3b, v184
	v_mul_f32_e32 v189, 0xbfb8aa3b, v185
	v_mul_f32_e32 v190, 0xbfb8aa3b, v186
	v_mul_f32_e32 v191, 0xbfb8aa3b, v187
	v_exp_f32_e32 v188, v188
	v_exp_f32_e32 v189, v189
	v_exp_f32_e32 v190, v190
	v_exp_f32_e32 v191, v191
	v_sub_f32_e32 v192, v40, v82
	v_sub_f32_e32 v193, v41, v82
	v_sub_f32_e32 v194, v42, v82
	v_sub_f32_e32 v195, v43, v82
	v_add_f32_e32 v188, 1.0, v188
	v_add_f32_e32 v189, 1.0, v189
	v_add_f32_e32 v190, 1.0, v190
	v_add_f32_e32 v191, 1.0, v191
	v_rcp_f32_e32 v188, v188
	v_rcp_f32_e32 v189, v189
	v_rcp_f32_e32 v190, v190
	v_rcp_f32_e32 v191, v191
	v_mul_f32_e32 v192, v192, v0
	v_mul_f32_e32 v193, v193, v0
	v_mul_f32_e32 v194, v194, v0
	v_mul_f32_e32 v195, v195, v0
	v_mul_f32_e32 v184, v184, v188
	v_mul_f32_e32 v185, v185, v189
	v_mul_f32_e32 v186, v186, v190
	v_mul_f32_e32 v187, v187, v191
	v_mul_f32_e32 v192, v130, v192
	v_mul_f32_e32 v193, v131, v193
	v_mul_f32_e32 v194, v132, v194
	v_mul_f32_e32 v195, v133, v195
	v_mul_f32_e32 v192, v192, v184
	v_mul_f32_e32 v193, v193, v185
	v_mul_f32_e32 v194, v194, v186
	v_mul_f32_e32 v195, v195, v187
	v_cvt_pk_bf16_f32 v192, v192, v193
	v_cvt_pk_bf16_f32 v193, v194, v195
	global_store_dwordx2 v[10:11], v[192:193], off offset:160
	s_waitcnt vmcnt(19)
	v_lshlrev_b32_e32 v184, 16, v2
	v_and_b32_e32 v185, 0xffff0000, v2
	v_lshlrev_b32_e32 v186, 16, v3
	v_and_b32_e32 v187, 0xffff0000, v3
	v_mul_f32_e32 v188, 0xbfb8aa3b, v184
	v_mul_f32_e32 v189, 0xbfb8aa3b, v185
	v_mul_f32_e32 v190, 0xbfb8aa3b, v186
	v_mul_f32_e32 v191, 0xbfb8aa3b, v187
	v_exp_f32_e32 v188, v188
	v_exp_f32_e32 v189, v189
	v_exp_f32_e32 v190, v190
	v_exp_f32_e32 v191, v191
	v_sub_f32_e32 v192, v44, v82
	v_sub_f32_e32 v193, v45, v82
	v_sub_f32_e32 v194, v46, v82
	v_sub_f32_e32 v195, v47, v82
	v_add_f32_e32 v188, 1.0, v188
	v_add_f32_e32 v189, 1.0, v189
	v_add_f32_e32 v190, 1.0, v190
	v_add_f32_e32 v191, 1.0, v191
	v_rcp_f32_e32 v188, v188
	v_rcp_f32_e32 v189, v189
	v_rcp_f32_e32 v190, v190
	v_rcp_f32_e32 v191, v191
	v_mul_f32_e32 v192, v192, v0
	v_mul_f32_e32 v193, v193, v0
	v_mul_f32_e32 v194, v194, v0
	v_mul_f32_e32 v195, v195, v0
	v_mul_f32_e32 v184, v184, v188
	v_mul_f32_e32 v185, v185, v189
	v_mul_f32_e32 v186, v186, v190
	v_mul_f32_e32 v187, v187, v191
	v_mul_f32_e32 v192, v134, v192
	v_mul_f32_e32 v193, v135, v193
	v_mul_f32_e32 v194, v136, v194
	v_mul_f32_e32 v195, v137, v195
	v_mul_f32_e32 v192, v192, v184
	v_mul_f32_e32 v193, v193, v185
	v_mul_f32_e32 v194, v194, v186
	v_mul_f32_e32 v195, v195, v187
	v_cvt_pk_bf16_f32 v192, v192, v193
	v_cvt_pk_bf16_f32 v193, v194, v195
	global_store_dwordx2 v[10:11], v[192:193], off offset:176
	s_waitcnt vmcnt(18)
	v_lshlrev_b32_e32 v184, 16, v4
	v_and_b32_e32 v185, 0xffff0000, v4
	v_lshlrev_b32_e32 v186, 16, v5
	v_and_b32_e32 v187, 0xffff0000, v5
	v_mul_f32_e32 v188, 0xbfb8aa3b, v184
	v_mul_f32_e32 v189, 0xbfb8aa3b, v185
	v_mul_f32_e32 v190, 0xbfb8aa3b, v186
	v_mul_f32_e32 v191, 0xbfb8aa3b, v187
	v_exp_f32_e32 v188, v188
	v_exp_f32_e32 v189, v189
	v_exp_f32_e32 v190, v190
	v_exp_f32_e32 v191, v191
	v_sub_f32_e32 v192, v16, v82
	v_sub_f32_e32 v193, v17, v82
	v_sub_f32_e32 v194, v18, v82
	v_sub_f32_e32 v195, v19, v82
	v_add_f32_e32 v188, 1.0, v188
	v_add_f32_e32 v189, 1.0, v189
	v_add_f32_e32 v190, 1.0, v190
	v_add_f32_e32 v191, 1.0, v191
	v_rcp_f32_e32 v188, v188
	v_rcp_f32_e32 v189, v189
	v_rcp_f32_e32 v190, v190
	v_rcp_f32_e32 v191, v191
	v_mul_f32_e32 v192, v192, v0
	v_mul_f32_e32 v193, v193, v0
	v_mul_f32_e32 v194, v194, v0
	v_mul_f32_e32 v195, v195, v0
	v_mul_f32_e32 v184, v184, v188
	v_mul_f32_e32 v185, v185, v189
	v_mul_f32_e32 v186, v186, v190
	v_mul_f32_e32 v187, v187, v191
	v_mul_f32_e32 v192, v138, v192
	v_mul_f32_e32 v193, v139, v193
	v_mul_f32_e32 v194, v140, v194
	v_mul_f32_e32 v195, v141, v195
	v_mul_f32_e32 v192, v192, v184
	v_mul_f32_e32 v193, v193, v185
	v_mul_f32_e32 v194, v194, v186
	v_mul_f32_e32 v195, v195, v187
	v_cvt_pk_bf16_f32 v192, v192, v193
	v_cvt_pk_bf16_f32 v193, v194, v195
	global_store_dwordx2 v[10:11], v[192:193], off offset:192
	s_waitcnt vmcnt(17)
	v_lshlrev_b32_e32 v184, 16, v12
	v_and_b32_e32 v185, 0xffff0000, v12
	v_lshlrev_b32_e32 v186, 16, v13
	v_and_b32_e32 v187, 0xffff0000, v13
	v_mul_f32_e32 v188, 0xbfb8aa3b, v184
	v_mul_f32_e32 v189, 0xbfb8aa3b, v185
	v_mul_f32_e32 v190, 0xbfb8aa3b, v186
	v_mul_f32_e32 v191, 0xbfb8aa3b, v187
	v_exp_f32_e32 v188, v188
	v_exp_f32_e32 v189, v189
	v_exp_f32_e32 v190, v190
	v_exp_f32_e32 v191, v191
	v_sub_f32_e32 v192, v20, v82
	v_sub_f32_e32 v193, v21, v82
	v_sub_f32_e32 v194, v22, v82
	v_sub_f32_e32 v195, v23, v82
	v_add_f32_e32 v188, 1.0, v188
	v_add_f32_e32 v189, 1.0, v189
	v_add_f32_e32 v190, 1.0, v190
	v_add_f32_e32 v191, 1.0, v191
	v_rcp_f32_e32 v188, v188
	v_rcp_f32_e32 v189, v189
	v_rcp_f32_e32 v190, v190
	v_rcp_f32_e32 v191, v191
	v_mul_f32_e32 v192, v192, v0
	v_mul_f32_e32 v193, v193, v0
	v_mul_f32_e32 v194, v194, v0
	v_mul_f32_e32 v195, v195, v0
	v_mul_f32_e32 v184, v184, v188
	v_mul_f32_e32 v185, v185, v189
	v_mul_f32_e32 v186, v186, v190
	v_mul_f32_e32 v187, v187, v191
	v_mul_f32_e32 v192, v142, v192
	v_mul_f32_e32 v193, v143, v193
	v_mul_f32_e32 v194, v144, v194
	v_mul_f32_e32 v195, v145, v195
	v_mul_f32_e32 v192, v192, v184
	v_mul_f32_e32 v193, v193, v185
	v_mul_f32_e32 v194, v194, v186
	v_mul_f32_e32 v195, v195, v187
	v_cvt_pk_bf16_f32 v192, v192, v193
	v_cvt_pk_bf16_f32 v193, v194, v195
	global_store_dwordx2 v[10:11], v[192:193], off offset:208
	s_waitcnt vmcnt(16)
	v_lshlrev_b32_e32 v184, 16, v14
	v_and_b32_e32 v185, 0xffff0000, v14
	v_lshlrev_b32_e32 v186, 16, v15
	v_and_b32_e32 v187, 0xffff0000, v15
	v_mul_f32_e32 v188, 0xbfb8aa3b, v184
	v_mul_f32_e32 v189, 0xbfb8aa3b, v185
	v_mul_f32_e32 v190, 0xbfb8aa3b, v186
	v_mul_f32_e32 v191, 0xbfb8aa3b, v187
	v_exp_f32_e32 v188, v188
	v_exp_f32_e32 v189, v189
	v_exp_f32_e32 v190, v190
	v_exp_f32_e32 v191, v191
	v_sub_f32_e32 v192, v24, v82
	v_sub_f32_e32 v193, v25, v82
	v_sub_f32_e32 v194, v26, v82
	v_sub_f32_e32 v195, v27, v82
	v_add_f32_e32 v188, 1.0, v188
	v_add_f32_e32 v189, 1.0, v189
	v_add_f32_e32 v190, 1.0, v190
	v_add_f32_e32 v191, 1.0, v191
	v_rcp_f32_e32 v188, v188
	v_rcp_f32_e32 v189, v189
	v_rcp_f32_e32 v190, v190
	v_rcp_f32_e32 v191, v191
	v_mul_f32_e32 v192, v192, v0
	v_mul_f32_e32 v193, v193, v0
	v_mul_f32_e32 v194, v194, v0
	v_mul_f32_e32 v195, v195, v0
	v_mul_f32_e32 v184, v184, v188
	v_mul_f32_e32 v185, v185, v189
	v_mul_f32_e32 v186, v186, v190
	v_mul_f32_e32 v187, v187, v191
	v_mul_f32_e32 v192, v146, v192
	v_mul_f32_e32 v193, v147, v193
	v_mul_f32_e32 v194, v148, v194
	v_mul_f32_e32 v195, v149, v195
	v_mul_f32_e32 v192, v192, v184
	v_mul_f32_e32 v193, v193, v185
	v_mul_f32_e32 v194, v194, v186
	v_mul_f32_e32 v195, v195, v187
	v_cvt_pk_bf16_f32 v192, v192, v193
	v_cvt_pk_bf16_f32 v193, v194, v195
	global_store_dwordx2 v[10:11], v[192:193], off offset:224
	s_waitcnt vmcnt(15)
	v_lshlrev_b32_e32 v184, 16, v86
	v_and_b32_e32 v185, 0xffff0000, v86
	v_lshlrev_b32_e32 v186, 16, v87
	v_and_b32_e32 v187, 0xffff0000, v87
	v_mul_f32_e32 v188, 0xbfb8aa3b, v184
	v_mul_f32_e32 v189, 0xbfb8aa3b, v185
	v_mul_f32_e32 v190, 0xbfb8aa3b, v186
	v_mul_f32_e32 v191, 0xbfb8aa3b, v187
	v_exp_f32_e32 v188, v188
	v_exp_f32_e32 v189, v189
	v_exp_f32_e32 v190, v190
	v_exp_f32_e32 v191, v191
	v_sub_f32_e32 v192, v28, v82
	v_sub_f32_e32 v193, v29, v82
	v_sub_f32_e32 v194, v30, v82
	v_sub_f32_e32 v195, v31, v82
	v_add_f32_e32 v188, 1.0, v188
	v_add_f32_e32 v189, 1.0, v189
	v_add_f32_e32 v190, 1.0, v190
	v_add_f32_e32 v191, 1.0, v191
	v_rcp_f32_e32 v188, v188
	v_rcp_f32_e32 v189, v189
	v_rcp_f32_e32 v190, v190
	v_rcp_f32_e32 v191, v191
	v_mul_f32_e32 v192, v192, v0
	v_mul_f32_e32 v193, v193, v0
	v_mul_f32_e32 v194, v194, v0
	v_mul_f32_e32 v195, v195, v0
	v_mul_f32_e32 v184, v184, v188
	v_mul_f32_e32 v185, v185, v189
	v_mul_f32_e32 v186, v186, v190
	v_mul_f32_e32 v187, v187, v191
	v_mul_f32_e32 v192, v150, v192
	v_mul_f32_e32 v193, v151, v193
	v_mul_f32_e32 v194, v152, v194
	v_mul_f32_e32 v195, v153, v195
	v_mul_f32_e32 v192, v192, v184
	v_mul_f32_e32 v193, v193, v185
	v_mul_f32_e32 v194, v194, v186
	v_mul_f32_e32 v195, v195, v187
	v_cvt_pk_bf16_f32 v192, v192, v193
	v_cvt_pk_bf16_f32 v193, v194, v195
	global_store_dwordx2 v[10:11], v[192:193], off offset:240
	s_add_i32 s12, s12, s46
	s_cmpk_gt_i32 s12, 0x1ff
	s_barrier
	s_cbranch_scc1 .LBB0_903
